# scan inner loop re-laid out as 2 rows x 4 columns per lane using only lo-half broadcasts in packed f32 ops (non-zero op_sel on v_pk_*_f32 gave run-to-run differences); butterfly 16-lane DPP reductions
# baseline (speedup 1.0000x reference)
.LBB0_682:
	s_waitcnt lgkmcnt(0)
	s_barrier
	ds_read_b128 v[78:81], v189 offset:16384
	ds_read_b128 v[82:85], v189 offset:40960
	ds_read_b128 v[86:89], v189 offset:24576
	ds_read_b128 v[90:93], v189 offset:32768
	ds_read_b128 v[94:97], v189
	ds_read_b32 v98, v190 offset:8192
	ds_read_b32 v100, v210 offset:8192
	s_and_b64 vcc, exec, s[50:51]
	s_cbranch_vccz .Lscan_rev
	s_movk_i32 s12, 0x400
	v_mov_b32_e32 v207, v189
	v_mov_b32_e32 v208, v190
	v_mov_b32_e32 v209, v190
	v_mov_b32_e32 v211, v210
	s_waitcnt lgkmcnt(0)
	ds_read_b128 v[118:121], v207 offset:16640
	ds_read_b128 v[122:125], v207 offset:41216
	ds_read_b128 v[126:129], v207 offset:24832
	ds_read_b128 v[130:133], v207 offset:33024
	ds_read_b128 v[134:137], v207 offset:256
	ds_read_b32 v138, v208 offset:8448
	ds_read_b32 v140, v211 offset:8448
	v_pk_mul_f32 v[212:213], v[164:165], v[78:79]
	v_pk_mul_f32 v[78:79], v[168:169], v[78:79]
	v_pk_fma_f32 v[212:213], v[166:167], v[80:81], v[212:213]
	v_pk_fma_f32 v[78:79], v[170:171], v[80:81], v[78:79]
	v_add_f32_e32 v218, v212, v213
	v_add_f32_e32 v219, v78, v79
	v_pk_mul_f32 v[164:165], v[90:91], v[164:165]
	v_pk_mul_f32 v[166:167], v[92:93], v[166:167]
	v_add_f32_dpp v220, v219, v218 row_ror:8 row_mask:0xf bank_mask:0xf
	v_pk_mul_f32 v[168:169], v[90:91], v[168:169]
	v_pk_mul_f32 v[170:171], v[92:93], v[170:171]
	v_add_f32_dpp v220, v220, v220 quad_perm:[1,0,3,2] row_mask:0xf bank_mask:0xf
	v_pk_fma_f32 v[164:165], v[86:87], v[98:99], v[164:165] op_sel_hi:[1,0,1]
	v_pk_fma_f32 v[166:167], v[88:89], v[98:99], v[166:167] op_sel_hi:[1,0,1]
	v_add_f32_dpp v220, v220, v220 quad_perm:[2,3,0,1] row_mask:0xf bank_mask:0xf
	v_pk_fma_f32 v[168:169], v[86:87], v[100:101], v[168:169] op_sel_hi:[1,0,1]
	v_pk_fma_f32 v[170:171], v[88:89], v[100:101], v[170:171] op_sel_hi:[1,0,1]
	v_add_f32_dpp v220, v220, v220 row_half_mirror row_mask:0xf bank_mask:0xf
	s_nop 1
	v_mov_b32_dpp v222, v220 row_ror:8 row_mask:0xf bank_mask:0xf
	v_pk_fma_f32 v[164:165], v[82:83], v[220:221], v[164:165] op_sel_hi:[1,0,1] neg_lo:[0,1,0] neg_hi:[0,1,0]
	v_pk_fma_f32 v[166:167], v[84:85], v[220:221], v[166:167] op_sel_hi:[1,0,1] neg_lo:[0,1,0] neg_hi:[0,1,0]
	v_pk_fma_f32 v[168:169], v[82:83], v[222:223], v[168:169] op_sel_hi:[1,0,1] neg_lo:[0,1,0] neg_hi:[0,1,0]
	v_pk_fma_f32 v[170:171], v[84:85], v[222:223], v[170:171] op_sel_hi:[1,0,1] neg_lo:[0,1,0] neg_hi:[0,1,0]
	v_pk_mul_f32 v[216:217], v[164:165], v[94:95]
	v_pk_mul_f32 v[94:95], v[168:169], v[94:95]
	v_pk_fma_f32 v[216:217], v[166:167], v[96:97], v[216:217]
	v_pk_fma_f32 v[94:95], v[170:171], v[96:97], v[94:95]
	v_add_f32_e32 v226, v216, v217
	v_add_f32_e32 v227, v94, v95
	s_waitcnt lgkmcnt(0)
	ds_read_b128 v[78:81], v207 offset:16896
	ds_read_b128 v[82:85], v207 offset:41472
	ds_read_b128 v[86:89], v207 offset:25088
	ds_read_b128 v[90:93], v207 offset:33280
	ds_read_b128 v[94:97], v207 offset:512
	ds_read_b32 v98, v208 offset:8704
	ds_read_b32 v100, v211 offset:8704
	v_pk_mul_f32 v[212:213], v[164:165], v[118:119]
	v_pk_mul_f32 v[118:119], v[168:169], v[118:119]
	v_add_f32_dpp v224, v227, v226 row_ror:8 row_mask:0xf bank_mask:0xf
	v_pk_fma_f32 v[212:213], v[166:167], v[120:121], v[212:213]
	v_pk_fma_f32 v[118:119], v[170:171], v[120:121], v[118:119]
	v_add_f32_dpp v224, v224, v224 quad_perm:[1,0,3,2] row_mask:0xf bank_mask:0xf
	v_add_f32_e32 v218, v212, v213
	v_add_f32_e32 v219, v118, v119
	v_pk_mul_f32 v[164:165], v[130:131], v[164:165]
	v_add_f32_dpp v224, v224, v224 quad_perm:[2,3,0,1] row_mask:0xf bank_mask:0xf
	v_add_f32_dpp v220, v219, v218 row_ror:8 row_mask:0xf bank_mask:0xf
	v_pk_mul_f32 v[166:167], v[132:133], v[166:167]
	v_add_f32_dpp v224, v224, v224 row_half_mirror row_mask:0xf bank_mask:0xf
	v_add_f32_dpp v220, v220, v220 quad_perm:[1,0,3,2] row_mask:0xf bank_mask:0xf
	v_pk_mul_f32 v[168:169], v[130:131], v[168:169]
	v_pk_mul_f32 v[170:171], v[132:133], v[170:171]
	v_add_f32_dpp v220, v220, v220 quad_perm:[2,3,0,1] row_mask:0xf bank_mask:0xf
	ds_write_b32 v209, v224 offset:49152
	v_pk_fma_f32 v[164:165], v[126:127], v[138:139], v[164:165] op_sel_hi:[1,0,1]
	v_pk_fma_f32 v[166:167], v[128:129], v[138:139], v[166:167] op_sel_hi:[1,0,1]
	v_add_f32_dpp v220, v220, v220 row_half_mirror row_mask:0xf bank_mask:0xf
	v_pk_fma_f32 v[168:169], v[126:127], v[140:141], v[168:169] op_sel_hi:[1,0,1]
	v_pk_fma_f32 v[170:171], v[128:129], v[140:141], v[170:171] op_sel_hi:[1,0,1]
	v_mov_b32_dpp v222, v220 row_ror:8 row_mask:0xf bank_mask:0xf
	v_pk_fma_f32 v[164:165], v[122:123], v[220:221], v[164:165] op_sel_hi:[1,0,1] neg_lo:[0,1,0] neg_hi:[0,1,0]
	v_pk_fma_f32 v[166:167], v[124:125], v[220:221], v[166:167] op_sel_hi:[1,0,1] neg_lo:[0,1,0] neg_hi:[0,1,0]
	v_pk_fma_f32 v[168:169], v[122:123], v[222:223], v[168:169] op_sel_hi:[1,0,1] neg_lo:[0,1,0] neg_hi:[0,1,0]
	v_pk_fma_f32 v[170:171], v[124:125], v[222:223], v[170:171] op_sel_hi:[1,0,1] neg_lo:[0,1,0] neg_hi:[0,1,0]
	v_pk_mul_f32 v[216:217], v[164:165], v[134:135]
	v_pk_mul_f32 v[134:135], v[168:169], v[134:135]
	v_pk_fma_f32 v[216:217], v[166:167], v[136:137], v[216:217]
	v_pk_fma_f32 v[134:135], v[170:171], v[136:137], v[134:135]
	v_add_f32_e32 v226, v216, v217
	v_add_f32_e32 v227, v134, v135
	s_waitcnt lgkmcnt(0)
	ds_read_b128 v[118:121], v207 offset:17152
	ds_read_b128 v[122:125], v207 offset:41728
	ds_read_b128 v[126:129], v207 offset:25344
	ds_read_b128 v[130:133], v207 offset:33536
	ds_read_b128 v[134:137], v207 offset:768
	ds_read_b32 v138, v208 offset:8960
	ds_read_b32 v140, v211 offset:8960
	v_pk_mul_f32 v[212:213], v[164:165], v[78:79]
	v_pk_mul_f32 v[78:79], v[168:169], v[78:79]
	v_add_f32_dpp v224, v227, v226 row_ror:8 row_mask:0xf bank_mask:0xf
	v_pk_fma_f32 v[212:213], v[166:167], v[80:81], v[212:213]
	v_pk_fma_f32 v[78:79], v[170:171], v[80:81], v[78:79]
	v_add_f32_dpp v224, v224, v224 quad_perm:[1,0,3,2] row_mask:0xf bank_mask:0xf
	v_add_f32_e32 v218, v212, v213
	v_add_f32_e32 v219, v78, v79
	v_pk_mul_f32 v[164:165], v[90:91], v[164:165]
	v_add_f32_dpp v224, v224, v224 quad_perm:[2,3,0,1] row_mask:0xf bank_mask:0xf
	v_add_f32_dpp v220, v219, v218 row_ror:8 row_mask:0xf bank_mask:0xf
	v_pk_mul_f32 v[166:167], v[92:93], v[166:167]
	v_add_f32_dpp v224, v224, v224 row_half_mirror row_mask:0xf bank_mask:0xf
	v_add_f32_dpp v220, v220, v220 quad_perm:[1,0,3,2] row_mask:0xf bank_mask:0xf
	v_pk_mul_f32 v[168:169], v[90:91], v[168:169]
	v_pk_mul_f32 v[170:171], v[92:93], v[170:171]
	v_add_f32_dpp v220, v220, v220 quad_perm:[2,3,0,1] row_mask:0xf bank_mask:0xf
	ds_write_b32 v209, v224 offset:49408
	v_pk_fma_f32 v[164:165], v[86:87], v[98:99], v[164:165] op_sel_hi:[1,0,1]
	v_pk_fma_f32 v[166:167], v[88:89], v[98:99], v[166:167] op_sel_hi:[1,0,1]
	v_add_f32_dpp v220, v220, v220 row_half_mirror row_mask:0xf bank_mask:0xf
	v_pk_fma_f32 v[168:169], v[86:87], v[100:101], v[168:169] op_sel_hi:[1,0,1]
	v_pk_fma_f32 v[170:171], v[88:89], v[100:101], v[170:171] op_sel_hi:[1,0,1]
	v_mov_b32_dpp v222, v220 row_ror:8 row_mask:0xf bank_mask:0xf
	v_pk_fma_f32 v[164:165], v[82:83], v[220:221], v[164:165] op_sel_hi:[1,0,1] neg_lo:[0,1,0] neg_hi:[0,1,0]
	v_pk_fma_f32 v[166:167], v[84:85], v[220:221], v[166:167] op_sel_hi:[1,0,1] neg_lo:[0,1,0] neg_hi:[0,1,0]
	v_pk_fma_f32 v[168:169], v[82:83], v[222:223], v[168:169] op_sel_hi:[1,0,1] neg_lo:[0,1,0] neg_hi:[0,1,0]
	v_pk_fma_f32 v[170:171], v[84:85], v[222:223], v[170:171] op_sel_hi:[1,0,1] neg_lo:[0,1,0] neg_hi:[0,1,0]
	v_pk_mul_f32 v[216:217], v[164:165], v[94:95]
	v_pk_mul_f32 v[94:95], v[168:169], v[94:95]
	v_pk_fma_f32 v[216:217], v[166:167], v[96:97], v[216:217]
	v_pk_fma_f32 v[94:95], v[170:171], v[96:97], v[94:95]
	v_add_f32_e32 v226, v216, v217
	v_add_f32_e32 v227, v94, v95
	s_waitcnt lgkmcnt(0)
	v_add_u32_e32 v207, s12, v207
	v_add_u32_e32 v208, s12, v208
	v_add_u32_e32 v211, s12, v211
	ds_read_b128 v[78:81], v207 offset:16384
	ds_read_b128 v[82:85], v207 offset:40960
	ds_read_b128 v[86:89], v207 offset:24576
	ds_read_b128 v[90:93], v207 offset:32768
	ds_read_b128 v[94:97], v207 offset:0
	ds_read_b32 v98, v208 offset:8192
	ds_read_b32 v100, v211 offset:8192
	v_pk_mul_f32 v[212:213], v[164:165], v[118:119]
	v_pk_mul_f32 v[118:119], v[168:169], v[118:119]
	v_add_f32_dpp v224, v227, v226 row_ror:8 row_mask:0xf bank_mask:0xf
	v_pk_fma_f32 v[212:213], v[166:167], v[120:121], v[212:213]
	v_pk_fma_f32 v[118:119], v[170:171], v[120:121], v[118:119]
	v_add_f32_dpp v224, v224, v224 quad_perm:[1,0,3,2] row_mask:0xf bank_mask:0xf
	v_add_f32_e32 v218, v212, v213
	v_add_f32_e32 v219, v118, v119
	v_pk_mul_f32 v[164:165], v[130:131], v[164:165]
	v_add_f32_dpp v224, v224, v224 quad_perm:[2,3,0,1] row_mask:0xf bank_mask:0xf
	v_add_f32_dpp v220, v219, v218 row_ror:8 row_mask:0xf bank_mask:0xf
	v_pk_mul_f32 v[166:167], v[132:133], v[166:167]
	v_add_f32_dpp v224, v224, v224 row_half_mirror row_mask:0xf bank_mask:0xf
	v_add_f32_dpp v220, v220, v220 quad_perm:[1,0,3,2] row_mask:0xf bank_mask:0xf
	v_pk_mul_f32 v[168:169], v[130:131], v[168:169]
	v_pk_mul_f32 v[170:171], v[132:133], v[170:171]
	v_add_f32_dpp v220, v220, v220 quad_perm:[2,3,0,1] row_mask:0xf bank_mask:0xf
	ds_write_b32 v209, v224 offset:49664
	v_pk_fma_f32 v[164:165], v[126:127], v[138:139], v[164:165] op_sel_hi:[1,0,1]
	v_pk_fma_f32 v[166:167], v[128:129], v[138:139], v[166:167] op_sel_hi:[1,0,1]
	v_add_f32_dpp v220, v220, v220 row_half_mirror row_mask:0xf bank_mask:0xf
	v_pk_fma_f32 v[168:169], v[126:127], v[140:141], v[168:169] op_sel_hi:[1,0,1]
	v_pk_fma_f32 v[170:171], v[128:129], v[140:141], v[170:171] op_sel_hi:[1,0,1]
	v_mov_b32_dpp v222, v220 row_ror:8 row_mask:0xf bank_mask:0xf
	v_pk_fma_f32 v[164:165], v[122:123], v[220:221], v[164:165] op_sel_hi:[1,0,1] neg_lo:[0,1,0] neg_hi:[0,1,0]
	v_pk_fma_f32 v[166:167], v[124:125], v[220:221], v[166:167] op_sel_hi:[1,0,1] neg_lo:[0,1,0] neg_hi:[0,1,0]
	v_pk_fma_f32 v[168:169], v[122:123], v[222:223], v[168:169] op_sel_hi:[1,0,1] neg_lo:[0,1,0] neg_hi:[0,1,0]
	v_pk_fma_f32 v[170:171], v[124:125], v[222:223], v[170:171] op_sel_hi:[1,0,1] neg_lo:[0,1,0] neg_hi:[0,1,0]
	v_pk_mul_f32 v[216:217], v[164:165], v[134:135]
	v_pk_mul_f32 v[134:135], v[168:169], v[134:135]
	v_pk_fma_f32 v[216:217], v[166:167], v[136:137], v[216:217]
	v_pk_fma_f32 v[134:135], v[170:171], v[136:137], v[134:135]
	v_add_f32_e32 v226, v216, v217
	v_add_f32_e32 v227, v134, v135
	s_mov_b32 s11, 1
.Lscan_fwd_loop:
	s_waitcnt lgkmcnt(0)
	ds_read_b128 v[118:121], v207 offset:16640
	ds_read_b128 v[122:125], v207 offset:41216
	ds_read_b128 v[126:129], v207 offset:24832
	ds_read_b128 v[130:133], v207 offset:33024
	ds_read_b128 v[134:137], v207 offset:256
	ds_read_b32 v138, v208 offset:8448
	ds_read_b32 v140, v211 offset:8448
	v_pk_mul_f32 v[212:213], v[164:165], v[78:79]
	v_pk_mul_f32 v[78:79], v[168:169], v[78:79]
	v_add_f32_dpp v224, v227, v226 row_ror:8 row_mask:0xf bank_mask:0xf
	v_pk_fma_f32 v[212:213], v[166:167], v[80:81], v[212:213]
	v_pk_fma_f32 v[78:79], v[170:171], v[80:81], v[78:79]
	v_add_f32_dpp v224, v224, v224 quad_perm:[1,0,3,2] row_mask:0xf bank_mask:0xf
	v_add_f32_e32 v218, v212, v213
	v_add_f32_e32 v219, v78, v79
	v_pk_mul_f32 v[164:165], v[90:91], v[164:165]
	v_add_f32_dpp v224, v224, v224 quad_perm:[2,3,0,1] row_mask:0xf bank_mask:0xf
	v_add_f32_dpp v220, v219, v218 row_ror:8 row_mask:0xf bank_mask:0xf
	v_pk_mul_f32 v[166:167], v[92:93], v[166:167]
	v_add_f32_dpp v224, v224, v224 row_half_mirror row_mask:0xf bank_mask:0xf
	v_add_f32_dpp v220, v220, v220 quad_perm:[1,0,3,2] row_mask:0xf bank_mask:0xf
	v_pk_mul_f32 v[168:169], v[90:91], v[168:169]
	v_pk_mul_f32 v[170:171], v[92:93], v[170:171]
	v_add_f32_dpp v220, v220, v220 quad_perm:[2,3,0,1] row_mask:0xf bank_mask:0xf
	ds_write_b32 v209, v224 offset:49920
	v_add_u32_e32 v209, s12, v209
	v_pk_fma_f32 v[164:165], v[86:87], v[98:99], v[164:165] op_sel_hi:[1,0,1]
	v_pk_fma_f32 v[166:167], v[88:89], v[98:99], v[166:167] op_sel_hi:[1,0,1]
	v_add_f32_dpp v220, v220, v220 row_half_mirror row_mask:0xf bank_mask:0xf
	v_pk_fma_f32 v[168:169], v[86:87], v[100:101], v[168:169] op_sel_hi:[1,0,1]
	v_pk_fma_f32 v[170:171], v[88:89], v[100:101], v[170:171] op_sel_hi:[1,0,1]
	v_mov_b32_dpp v222, v220 row_ror:8 row_mask:0xf bank_mask:0xf
	v_pk_fma_f32 v[164:165], v[82:83], v[220:221], v[164:165] op_sel_hi:[1,0,1] neg_lo:[0,1,0] neg_hi:[0,1,0]
	v_pk_fma_f32 v[166:167], v[84:85], v[220:221], v[166:167] op_sel_hi:[1,0,1] neg_lo:[0,1,0] neg_hi:[0,1,0]
	v_pk_fma_f32 v[168:169], v[82:83], v[222:223], v[168:169] op_sel_hi:[1,0,1] neg_lo:[0,1,0] neg_hi:[0,1,0]
	v_pk_fma_f32 v[170:171], v[84:85], v[222:223], v[170:171] op_sel_hi:[1,0,1] neg_lo:[0,1,0] neg_hi:[0,1,0]
	v_pk_mul_f32 v[216:217], v[164:165], v[94:95]
	v_pk_mul_f32 v[94:95], v[168:169], v[94:95]
	v_pk_fma_f32 v[216:217], v[166:167], v[96:97], v[216:217]
	v_pk_fma_f32 v[94:95], v[170:171], v[96:97], v[94:95]
	v_add_f32_e32 v226, v216, v217
	v_add_f32_e32 v227, v94, v95
	s_waitcnt lgkmcnt(0)
	ds_read_b128 v[78:81], v207 offset:16896
	ds_read_b128 v[82:85], v207 offset:41472
	ds_read_b128 v[86:89], v207 offset:25088
	ds_read_b128 v[90:93], v207 offset:33280
	ds_read_b128 v[94:97], v207 offset:512
	ds_read_b32 v98, v208 offset:8704
	ds_read_b32 v100, v211 offset:8704
	v_pk_mul_f32 v[212:213], v[164:165], v[118:119]
	v_pk_mul_f32 v[118:119], v[168:169], v[118:119]
	v_add_f32_dpp v224, v227, v226 row_ror:8 row_mask:0xf bank_mask:0xf
	v_pk_fma_f32 v[212:213], v[166:167], v[120:121], v[212:213]
	v_pk_fma_f32 v[118:119], v[170:171], v[120:121], v[118:119]
	v_add_f32_dpp v224, v224, v224 quad_perm:[1,0,3,2] row_mask:0xf bank_mask:0xf
	v_add_f32_e32 v218, v212, v213
	v_add_f32_e32 v219, v118, v119
	v_pk_mul_f32 v[164:165], v[130:131], v[164:165]
	v_add_f32_dpp v224, v224, v224 quad_perm:[2,3,0,1] row_mask:0xf bank_mask:0xf
	v_add_f32_dpp v220, v219, v218 row_ror:8 row_mask:0xf bank_mask:0xf
	v_pk_mul_f32 v[166:167], v[132:133], v[166:167]
	v_add_f32_dpp v224, v224, v224 row_half_mirror row_mask:0xf bank_mask:0xf
	v_add_f32_dpp v220, v220, v220 quad_perm:[1,0,3,2] row_mask:0xf bank_mask:0xf
	v_pk_mul_f32 v[168:169], v[130:131], v[168:169]
	v_pk_mul_f32 v[170:171], v[132:133], v[170:171]
	v_add_f32_dpp v220, v220, v220 quad_perm:[2,3,0,1] row_mask:0xf bank_mask:0xf
	ds_write_b32 v209, v224 offset:49152
	v_pk_fma_f32 v[164:165], v[126:127], v[138:139], v[164:165] op_sel_hi:[1,0,1]
	v_pk_fma_f32 v[166:167], v[128:129], v[138:139], v[166:167] op_sel_hi:[1,0,1]
	v_add_f32_dpp v220, v220, v220 row_half_mirror row_mask:0xf bank_mask:0xf
	v_pk_fma_f32 v[168:169], v[126:127], v[140:141], v[168:169] op_sel_hi:[1,0,1]
	v_pk_fma_f32 v[170:171], v[128:129], v[140:141], v[170:171] op_sel_hi:[1,0,1]
	v_mov_b32_dpp v222, v220 row_ror:8 row_mask:0xf bank_mask:0xf
	v_pk_fma_f32 v[164:165], v[122:123], v[220:221], v[164:165] op_sel_hi:[1,0,1] neg_lo:[0,1,0] neg_hi:[0,1,0]
	v_pk_fma_f32 v[166:167], v[124:125], v[220:221], v[166:167] op_sel_hi:[1,0,1] neg_lo:[0,1,0] neg_hi:[0,1,0]
	v_pk_fma_f32 v[168:169], v[122:123], v[222:223], v[168:169] op_sel_hi:[1,0,1] neg_lo:[0,1,0] neg_hi:[0,1,0]
	v_pk_fma_f32 v[170:171], v[124:125], v[222:223], v[170:171] op_sel_hi:[1,0,1] neg_lo:[0,1,0] neg_hi:[0,1,0]
	v_pk_mul_f32 v[216:217], v[164:165], v[134:135]
	v_pk_mul_f32 v[134:135], v[168:169], v[134:135]
	v_pk_fma_f32 v[216:217], v[166:167], v[136:137], v[216:217]
	v_pk_fma_f32 v[134:135], v[170:171], v[136:137], v[134:135]
	v_add_f32_e32 v226, v216, v217
	v_add_f32_e32 v227, v134, v135
	s_waitcnt lgkmcnt(0)
	ds_read_b128 v[118:121], v207 offset:17152
	ds_read_b128 v[122:125], v207 offset:41728
	ds_read_b128 v[126:129], v207 offset:25344
	ds_read_b128 v[130:133], v207 offset:33536
	ds_read_b128 v[134:137], v207 offset:768
	ds_read_b32 v138, v208 offset:8960
	ds_read_b32 v140, v211 offset:8960
	v_pk_mul_f32 v[212:213], v[164:165], v[78:79]
	v_pk_mul_f32 v[78:79], v[168:169], v[78:79]
	v_add_f32_dpp v224, v227, v226 row_ror:8 row_mask:0xf bank_mask:0xf
	v_pk_fma_f32 v[212:213], v[166:167], v[80:81], v[212:213]
	v_pk_fma_f32 v[78:79], v[170:171], v[80:81], v[78:79]
	v_add_f32_dpp v224, v224, v224 quad_perm:[1,0,3,2] row_mask:0xf bank_mask:0xf
	v_add_f32_e32 v218, v212, v213
	v_add_f32_e32 v219, v78, v79
	v_pk_mul_f32 v[164:165], v[90:91], v[164:165]
	v_add_f32_dpp v224, v224, v224 quad_perm:[2,3,0,1] row_mask:0xf bank_mask:0xf
	v_add_f32_dpp v220, v219, v218 row_ror:8 row_mask:0xf bank_mask:0xf
	v_pk_mul_f32 v[166:167], v[92:93], v[166:167]
	v_add_f32_dpp v224, v224, v224 row_half_mirror row_mask:0xf bank_mask:0xf
	v_add_f32_dpp v220, v220, v220 quad_perm:[1,0,3,2] row_mask:0xf bank_mask:0xf
	v_pk_mul_f32 v[168:169], v[90:91], v[168:169]
	v_pk_mul_f32 v[170:171], v[92:93], v[170:171]
	v_add_f32_dpp v220, v220, v220 quad_perm:[2,3,0,1] row_mask:0xf bank_mask:0xf
	ds_write_b32 v209, v224 offset:49408
	v_pk_fma_f32 v[164:165], v[86:87], v[98:99], v[164:165] op_sel_hi:[1,0,1]
	v_pk_fma_f32 v[166:167], v[88:89], v[98:99], v[166:167] op_sel_hi:[1,0,1]
	v_add_f32_dpp v220, v220, v220 row_half_mirror row_mask:0xf bank_mask:0xf
	v_pk_fma_f32 v[168:169], v[86:87], v[100:101], v[168:169] op_sel_hi:[1,0,1]
	v_pk_fma_f32 v[170:171], v[88:89], v[100:101], v[170:171] op_sel_hi:[1,0,1]
	v_mov_b32_dpp v222, v220 row_ror:8 row_mask:0xf bank_mask:0xf
	v_pk_fma_f32 v[164:165], v[82:83], v[220:221], v[164:165] op_sel_hi:[1,0,1] neg_lo:[0,1,0] neg_hi:[0,1,0]
	v_pk_fma_f32 v[166:167], v[84:85], v[220:221], v[166:167] op_sel_hi:[1,0,1] neg_lo:[0,1,0] neg_hi:[0,1,0]
	v_pk_fma_f32 v[168:169], v[82:83], v[222:223], v[168:169] op_sel_hi:[1,0,1] neg_lo:[0,1,0] neg_hi:[0,1,0]
	v_pk_fma_f32 v[170:171], v[84:85], v[222:223], v[170:171] op_sel_hi:[1,0,1] neg_lo:[0,1,0] neg_hi:[0,1,0]
	v_pk_mul_f32 v[216:217], v[164:165], v[94:95]
	v_pk_mul_f32 v[94:95], v[168:169], v[94:95]
	v_pk_fma_f32 v[216:217], v[166:167], v[96:97], v[216:217]
	v_pk_fma_f32 v[94:95], v[170:171], v[96:97], v[94:95]
	v_add_f32_e32 v226, v216, v217
	v_add_f32_e32 v227, v94, v95
	s_waitcnt lgkmcnt(0)
	s_cmp_eq_u32 s11, 7
	s_cbranch_scc1 .Lscan_fwd_nopf
	v_add_u32_e32 v207, s12, v207
	v_add_u32_e32 v208, s12, v208
	v_add_u32_e32 v211, s12, v211
	ds_read_b128 v[78:81], v207 offset:16384
	ds_read_b128 v[82:85], v207 offset:40960
	ds_read_b128 v[86:89], v207 offset:24576
	ds_read_b128 v[90:93], v207 offset:32768
	ds_read_b128 v[94:97], v207 offset:0
	ds_read_b32 v98, v208 offset:8192
	ds_read_b32 v100, v211 offset:8192
.Lscan_fwd_nopf:
	v_pk_mul_f32 v[212:213], v[164:165], v[118:119]
	v_pk_mul_f32 v[118:119], v[168:169], v[118:119]
	v_add_f32_dpp v224, v227, v226 row_ror:8 row_mask:0xf bank_mask:0xf
	v_pk_fma_f32 v[212:213], v[166:167], v[120:121], v[212:213]
	v_pk_fma_f32 v[118:119], v[170:171], v[120:121], v[118:119]
	v_add_f32_dpp v224, v224, v224 quad_perm:[1,0,3,2] row_mask:0xf bank_mask:0xf
	v_add_f32_e32 v218, v212, v213
	v_add_f32_e32 v219, v118, v119
	v_pk_mul_f32 v[164:165], v[130:131], v[164:165]
	v_add_f32_dpp v224, v224, v224 quad_perm:[2,3,0,1] row_mask:0xf bank_mask:0xf
	v_add_f32_dpp v220, v219, v218 row_ror:8 row_mask:0xf bank_mask:0xf
	v_pk_mul_f32 v[166:167], v[132:133], v[166:167]
	v_add_f32_dpp v224, v224, v224 row_half_mirror row_mask:0xf bank_mask:0xf
	v_add_f32_dpp v220, v220, v220 quad_perm:[1,0,3,2] row_mask:0xf bank_mask:0xf
	v_pk_mul_f32 v[168:169], v[130:131], v[168:169]
	v_pk_mul_f32 v[170:171], v[132:133], v[170:171]
	v_add_f32_dpp v220, v220, v220 quad_perm:[2,3,0,1] row_mask:0xf bank_mask:0xf
	ds_write_b32 v209, v224 offset:49664
	v_pk_fma_f32 v[164:165], v[126:127], v[138:139], v[164:165] op_sel_hi:[1,0,1]
	v_pk_fma_f32 v[166:167], v[128:129], v[138:139], v[166:167] op_sel_hi:[1,0,1]
	v_add_f32_dpp v220, v220, v220 row_half_mirror row_mask:0xf bank_mask:0xf
	v_pk_fma_f32 v[168:169], v[126:127], v[140:141], v[168:169] op_sel_hi:[1,0,1]
	v_pk_fma_f32 v[170:171], v[128:129], v[140:141], v[170:171] op_sel_hi:[1,0,1]
	v_mov_b32_dpp v222, v220 row_ror:8 row_mask:0xf bank_mask:0xf
	v_pk_fma_f32 v[164:165], v[122:123], v[220:221], v[164:165] op_sel_hi:[1,0,1] neg_lo:[0,1,0] neg_hi:[0,1,0]
	v_pk_fma_f32 v[166:167], v[124:125], v[220:221], v[166:167] op_sel_hi:[1,0,1] neg_lo:[0,1,0] neg_hi:[0,1,0]
	v_pk_fma_f32 v[168:169], v[122:123], v[222:223], v[168:169] op_sel_hi:[1,0,1] neg_lo:[0,1,0] neg_hi:[0,1,0]
	v_pk_fma_f32 v[170:171], v[124:125], v[222:223], v[170:171] op_sel_hi:[1,0,1] neg_lo:[0,1,0] neg_hi:[0,1,0]
	v_pk_mul_f32 v[216:217], v[164:165], v[134:135]
	v_pk_mul_f32 v[134:135], v[168:169], v[134:135]
	v_pk_fma_f32 v[216:217], v[166:167], v[136:137], v[216:217]
	v_pk_fma_f32 v[134:135], v[170:171], v[136:137], v[134:135]
	v_add_f32_e32 v226, v216, v217
	v_add_f32_e32 v227, v134, v135
	s_add_i32 s11, s11, 1
	s_cmp_lg_u32 s11, 8
	s_cbranch_scc1 .Lscan_fwd_loop
	s_nop 1
	v_add_f32_dpp v224, v227, v226 row_ror:8 row_mask:0xf bank_mask:0xf
	s_nop 1
	v_add_f32_dpp v224, v224, v224 quad_perm:[1,0,3,2] row_mask:0xf bank_mask:0xf
	s_nop 1
	v_add_f32_dpp v224, v224, v224 quad_perm:[2,3,0,1] row_mask:0xf bank_mask:0xf
	s_nop 1
	v_add_f32_dpp v224, v224, v224 row_half_mirror row_mask:0xf bank_mask:0xf
	ds_write_b32 v209, v224 offset:49920
	s_branch .LBB0_691
.Lscan_rev:
	s_mov_b32 s12, 0xfffffc00
	v_add_u32_e32 v207, 0xfffffd00, v189
	v_add_u32_e32 v208, 0xfffffd00, v190
	v_add_u32_e32 v209, 0xfffffd00, v190
	v_add_u32_e32 v211, 0xfffffd00, v210
	s_waitcnt lgkmcnt(0)
	ds_read_b128 v[118:121], v207 offset:16896
	ds_read_b128 v[122:125], v207 offset:41472
	ds_read_b128 v[126:129], v207 offset:25088
	ds_read_b128 v[130:133], v207 offset:33280
	ds_read_b128 v[134:137], v207 offset:512
	ds_read_b32 v138, v208 offset:8704
	ds_read_b32 v140, v211 offset:8704
	v_pk_mul_f32 v[212:213], v[164:165], v[78:79]
	v_pk_mul_f32 v[78:79], v[168:169], v[78:79]
	v_pk_fma_f32 v[212:213], v[166:167], v[80:81], v[212:213]
	v_pk_fma_f32 v[78:79], v[170:171], v[80:81], v[78:79]
	v_add_f32_e32 v218, v212, v213
	v_add_f32_e32 v219, v78, v79
	v_pk_mul_f32 v[164:165], v[90:91], v[164:165]
	v_pk_mul_f32 v[166:167], v[92:93], v[166:167]
	v_add_f32_dpp v220, v219, v218 row_ror:8 row_mask:0xf bank_mask:0xf
	v_pk_mul_f32 v[168:169], v[90:91], v[168:169]
	v_pk_mul_f32 v[170:171], v[92:93], v[170:171]
	v_add_f32_dpp v220, v220, v220 quad_perm:[1,0,3,2] row_mask:0xf bank_mask:0xf
	v_pk_fma_f32 v[164:165], v[86:87], v[98:99], v[164:165] op_sel_hi:[1,0,1]
	v_pk_fma_f32 v[166:167], v[88:89], v[98:99], v[166:167] op_sel_hi:[1,0,1]
	v_add_f32_dpp v220, v220, v220 quad_perm:[2,3,0,1] row_mask:0xf bank_mask:0xf
	v_pk_fma_f32 v[168:169], v[86:87], v[100:101], v[168:169] op_sel_hi:[1,0,1]
	v_pk_fma_f32 v[170:171], v[88:89], v[100:101], v[170:171] op_sel_hi:[1,0,1]
	v_add_f32_dpp v220, v220, v220 row_half_mirror row_mask:0xf bank_mask:0xf
	s_nop 1
	v_mov_b32_dpp v222, v220 row_ror:8 row_mask:0xf bank_mask:0xf
	v_pk_fma_f32 v[164:165], v[82:83], v[220:221], v[164:165] op_sel_hi:[1,0,1] neg_lo:[0,1,0] neg_hi:[0,1,0]
	v_pk_fma_f32 v[166:167], v[84:85], v[220:221], v[166:167] op_sel_hi:[1,0,1] neg_lo:[0,1,0] neg_hi:[0,1,0]
	v_pk_fma_f32 v[168:169], v[82:83], v[222:223], v[168:169] op_sel_hi:[1,0,1] neg_lo:[0,1,0] neg_hi:[0,1,0]
	v_pk_fma_f32 v[170:171], v[84:85], v[222:223], v[170:171] op_sel_hi:[1,0,1] neg_lo:[0,1,0] neg_hi:[0,1,0]
	v_pk_mul_f32 v[216:217], v[164:165], v[94:95]
	v_pk_mul_f32 v[94:95], v[168:169], v[94:95]
	v_pk_fma_f32 v[216:217], v[166:167], v[96:97], v[216:217]
	v_pk_fma_f32 v[94:95], v[170:171], v[96:97], v[94:95]
	v_add_f32_e32 v226, v216, v217
	v_add_f32_e32 v227, v94, v95
	s_waitcnt lgkmcnt(0)
	ds_read_b128 v[78:81], v207 offset:16640
	ds_read_b128 v[82:85], v207 offset:41216
	ds_read_b128 v[86:89], v207 offset:24832
	ds_read_b128 v[90:93], v207 offset:33024
	ds_read_b128 v[94:97], v207 offset:256
	ds_read_b32 v98, v208 offset:8448
	ds_read_b32 v100, v211 offset:8448
	v_pk_mul_f32 v[212:213], v[164:165], v[118:119]
	v_pk_mul_f32 v[118:119], v[168:169], v[118:119]
	v_add_f32_dpp v224, v227, v226 row_ror:8 row_mask:0xf bank_mask:0xf
	v_pk_fma_f32 v[212:213], v[166:167], v[120:121], v[212:213]
	v_pk_fma_f32 v[118:119], v[170:171], v[120:121], v[118:119]
	v_add_f32_dpp v224, v224, v224 quad_perm:[1,0,3,2] row_mask:0xf bank_mask:0xf
	v_add_f32_e32 v218, v212, v213
	v_add_f32_e32 v219, v118, v119
	v_pk_mul_f32 v[164:165], v[130:131], v[164:165]
	v_add_f32_dpp v224, v224, v224 quad_perm:[2,3,0,1] row_mask:0xf bank_mask:0xf
	v_add_f32_dpp v220, v219, v218 row_ror:8 row_mask:0xf bank_mask:0xf
	v_pk_mul_f32 v[166:167], v[132:133], v[166:167]
	v_add_f32_dpp v224, v224, v224 row_half_mirror row_mask:0xf bank_mask:0xf
	v_add_f32_dpp v220, v220, v220 quad_perm:[1,0,3,2] row_mask:0xf bank_mask:0xf
	v_pk_mul_f32 v[168:169], v[130:131], v[168:169]
	v_pk_mul_f32 v[170:171], v[132:133], v[170:171]
	v_add_f32_dpp v220, v220, v220 quad_perm:[2,3,0,1] row_mask:0xf bank_mask:0xf
	ds_write_b32 v209, v224 offset:49920
	v_pk_fma_f32 v[164:165], v[126:127], v[138:139], v[164:165] op_sel_hi:[1,0,1]
	v_pk_fma_f32 v[166:167], v[128:129], v[138:139], v[166:167] op_sel_hi:[1,0,1]
	v_add_f32_dpp v220, v220, v220 row_half_mirror row_mask:0xf bank_mask:0xf
	v_pk_fma_f32 v[168:169], v[126:127], v[140:141], v[168:169] op_sel_hi:[1,0,1]
	v_pk_fma_f32 v[170:171], v[128:129], v[140:141], v[170:171] op_sel_hi:[1,0,1]
	v_mov_b32_dpp v222, v220 row_ror:8 row_mask:0xf bank_mask:0xf
	v_pk_fma_f32 v[164:165], v[122:123], v[220:221], v[164:165] op_sel_hi:[1,0,1] neg_lo:[0,1,0] neg_hi:[0,1,0]
	v_pk_fma_f32 v[166:167], v[124:125], v[220:221], v[166:167] op_sel_hi:[1,0,1] neg_lo:[0,1,0] neg_hi:[0,1,0]
	v_pk_fma_f32 v[168:169], v[122:123], v[222:223], v[168:169] op_sel_hi:[1,0,1] neg_lo:[0,1,0] neg_hi:[0,1,0]
	v_pk_fma_f32 v[170:171], v[124:125], v[222:223], v[170:171] op_sel_hi:[1,0,1] neg_lo:[0,1,0] neg_hi:[0,1,0]
	v_pk_mul_f32 v[216:217], v[164:165], v[134:135]
	v_pk_mul_f32 v[134:135], v[168:169], v[134:135]
	v_pk_fma_f32 v[216:217], v[166:167], v[136:137], v[216:217]
	v_pk_fma_f32 v[134:135], v[170:171], v[136:137], v[134:135]
	v_add_f32_e32 v226, v216, v217
	v_add_f32_e32 v227, v134, v135
	s_waitcnt lgkmcnt(0)
	ds_read_b128 v[118:121], v207 offset:16384
	ds_read_b128 v[122:125], v207 offset:40960
	ds_read_b128 v[126:129], v207 offset:24576
	ds_read_b128 v[130:133], v207 offset:32768
	ds_read_b128 v[134:137], v207 offset:0
	ds_read_b32 v138, v208 offset:8192
	ds_read_b32 v140, v211 offset:8192
	v_pk_mul_f32 v[212:213], v[164:165], v[78:79]
	v_pk_mul_f32 v[78:79], v[168:169], v[78:79]
	v_add_f32_dpp v224, v227, v226 row_ror:8 row_mask:0xf bank_mask:0xf
	v_pk_fma_f32 v[212:213], v[166:167], v[80:81], v[212:213]
	v_pk_fma_f32 v[78:79], v[170:171], v[80:81], v[78:79]
	v_add_f32_dpp v224, v224, v224 quad_perm:[1,0,3,2] row_mask:0xf bank_mask:0xf
	v_add_f32_e32 v218, v212, v213
	v_add_f32_e32 v219, v78, v79
	v_pk_mul_f32 v[164:165], v[90:91], v[164:165]
	v_add_f32_dpp v224, v224, v224 quad_perm:[2,3,0,1] row_mask:0xf bank_mask:0xf
	v_add_f32_dpp v220, v219, v218 row_ror:8 row_mask:0xf bank_mask:0xf
	v_pk_mul_f32 v[166:167], v[92:93], v[166:167]
	v_add_f32_dpp v224, v224, v224 row_half_mirror row_mask:0xf bank_mask:0xf
	v_add_f32_dpp v220, v220, v220 quad_perm:[1,0,3,2] row_mask:0xf bank_mask:0xf
	v_pk_mul_f32 v[168:169], v[90:91], v[168:169]
	v_pk_mul_f32 v[170:171], v[92:93], v[170:171]
	v_add_f32_dpp v220, v220, v220 quad_perm:[2,3,0,1] row_mask:0xf bank_mask:0xf
	ds_write_b32 v209, v224 offset:49664
	v_pk_fma_f32 v[164:165], v[86:87], v[98:99], v[164:165] op_sel_hi:[1,0,1]
	v_pk_fma_f32 v[166:167], v[88:89], v[98:99], v[166:167] op_sel_hi:[1,0,1]
	v_add_f32_dpp v220, v220, v220 row_half_mirror row_mask:0xf bank_mask:0xf
	v_pk_fma_f32 v[168:169], v[86:87], v[100:101], v[168:169] op_sel_hi:[1,0,1]
	v_pk_fma_f32 v[170:171], v[88:89], v[100:101], v[170:171] op_sel_hi:[1,0,1]
	v_mov_b32_dpp v222, v220 row_ror:8 row_mask:0xf bank_mask:0xf
	v_pk_fma_f32 v[164:165], v[82:83], v[220:221], v[164:165] op_sel_hi:[1,0,1] neg_lo:[0,1,0] neg_hi:[0,1,0]
	v_pk_fma_f32 v[166:167], v[84:85], v[220:221], v[166:167] op_sel_hi:[1,0,1] neg_lo:[0,1,0] neg_hi:[0,1,0]
	v_pk_fma_f32 v[168:169], v[82:83], v[222:223], v[168:169] op_sel_hi:[1,0,1] neg_lo:[0,1,0] neg_hi:[0,1,0]
	v_pk_fma_f32 v[170:171], v[84:85], v[222:223], v[170:171] op_sel_hi:[1,0,1] neg_lo:[0,1,0] neg_hi:[0,1,0]
	v_pk_mul_f32 v[216:217], v[164:165], v[94:95]
	v_pk_mul_f32 v[94:95], v[168:169], v[94:95]
	v_pk_fma_f32 v[216:217], v[166:167], v[96:97], v[216:217]
	v_pk_fma_f32 v[94:95], v[170:171], v[96:97], v[94:95]
	v_add_f32_e32 v226, v216, v217
	v_add_f32_e32 v227, v94, v95
	s_waitcnt lgkmcnt(0)
	v_add_u32_e32 v207, s12, v207
	v_add_u32_e32 v208, s12, v208
	v_add_u32_e32 v211, s12, v211
	ds_read_b128 v[78:81], v207 offset:17152
	ds_read_b128 v[82:85], v207 offset:41728
	ds_read_b128 v[86:89], v207 offset:25344
	ds_read_b128 v[90:93], v207 offset:33536
	ds_read_b128 v[94:97], v207 offset:768
	ds_read_b32 v98, v208 offset:8960
	ds_read_b32 v100, v211 offset:8960
	v_pk_mul_f32 v[212:213], v[164:165], v[118:119]
	v_pk_mul_f32 v[118:119], v[168:169], v[118:119]
	v_add_f32_dpp v224, v227, v226 row_ror:8 row_mask:0xf bank_mask:0xf
	v_pk_fma_f32 v[212:213], v[166:167], v[120:121], v[212:213]
	v_pk_fma_f32 v[118:119], v[170:171], v[120:121], v[118:119]
	v_add_f32_dpp v224, v224, v224 quad_perm:[1,0,3,2] row_mask:0xf bank_mask:0xf
	v_add_f32_e32 v218, v212, v213
	v_add_f32_e32 v219, v118, v119
	v_pk_mul_f32 v[164:165], v[130:131], v[164:165]
	v_add_f32_dpp v224, v224, v224 quad_perm:[2,3,0,1] row_mask:0xf bank_mask:0xf
	v_add_f32_dpp v220, v219, v218 row_ror:8 row_mask:0xf bank_mask:0xf
	v_pk_mul_f32 v[166:167], v[132:133], v[166:167]
	v_add_f32_dpp v224, v224, v224 row_half_mirror row_mask:0xf bank_mask:0xf
	v_add_f32_dpp v220, v220, v220 quad_perm:[1,0,3,2] row_mask:0xf bank_mask:0xf
	v_pk_mul_f32 v[168:169], v[130:131], v[168:169]
	v_pk_mul_f32 v[170:171], v[132:133], v[170:171]
	v_add_f32_dpp v220, v220, v220 quad_perm:[2,3,0,1] row_mask:0xf bank_mask:0xf
	ds_write_b32 v209, v224 offset:49408
	v_pk_fma_f32 v[164:165], v[126:127], v[138:139], v[164:165] op_sel_hi:[1,0,1]
	v_pk_fma_f32 v[166:167], v[128:129], v[138:139], v[166:167] op_sel_hi:[1,0,1]
	v_add_f32_dpp v220, v220, v220 row_half_mirror row_mask:0xf bank_mask:0xf
	v_pk_fma_f32 v[168:169], v[126:127], v[140:141], v[168:169] op_sel_hi:[1,0,1]
	v_pk_fma_f32 v[170:171], v[128:129], v[140:141], v[170:171] op_sel_hi:[1,0,1]
	v_mov_b32_dpp v222, v220 row_ror:8 row_mask:0xf bank_mask:0xf
	v_pk_fma_f32 v[164:165], v[122:123], v[220:221], v[164:165] op_sel_hi:[1,0,1] neg_lo:[0,1,0] neg_hi:[0,1,0]
	v_pk_fma_f32 v[166:167], v[124:125], v[220:221], v[166:167] op_sel_hi:[1,0,1] neg_lo:[0,1,0] neg_hi:[0,1,0]
	v_pk_fma_f32 v[168:169], v[122:123], v[222:223], v[168:169] op_sel_hi:[1,0,1] neg_lo:[0,1,0] neg_hi:[0,1,0]
	v_pk_fma_f32 v[170:171], v[124:125], v[222:223], v[170:171] op_sel_hi:[1,0,1] neg_lo:[0,1,0] neg_hi:[0,1,0]
	v_pk_mul_f32 v[216:217], v[164:165], v[134:135]
	v_pk_mul_f32 v[134:135], v[168:169], v[134:135]
	v_pk_fma_f32 v[216:217], v[166:167], v[136:137], v[216:217]
	v_pk_fma_f32 v[134:135], v[170:171], v[136:137], v[134:135]
	v_add_f32_e32 v226, v216, v217
	v_add_f32_e32 v227, v134, v135
	s_mov_b32 s11, 1
.Lscan_rev_loop:
	s_waitcnt lgkmcnt(0)
	ds_read_b128 v[118:121], v207 offset:16896
	ds_read_b128 v[122:125], v207 offset:41472
	ds_read_b128 v[126:129], v207 offset:25088
	ds_read_b128 v[130:133], v207 offset:33280
	ds_read_b128 v[134:137], v207 offset:512
	ds_read_b32 v138, v208 offset:8704
	ds_read_b32 v140, v211 offset:8704
	v_pk_mul_f32 v[212:213], v[164:165], v[78:79]
	v_pk_mul_f32 v[78:79], v[168:169], v[78:79]
	v_add_f32_dpp v224, v227, v226 row_ror:8 row_mask:0xf bank_mask:0xf
	v_pk_fma_f32 v[212:213], v[166:167], v[80:81], v[212:213]
	v_pk_fma_f32 v[78:79], v[170:171], v[80:81], v[78:79]
	v_add_f32_dpp v224, v224, v224 quad_perm:[1,0,3,2] row_mask:0xf bank_mask:0xf
	v_add_f32_e32 v218, v212, v213
	v_add_f32_e32 v219, v78, v79
	v_pk_mul_f32 v[164:165], v[90:91], v[164:165]
	v_add_f32_dpp v224, v224, v224 quad_perm:[2,3,0,1] row_mask:0xf bank_mask:0xf
	v_add_f32_dpp v220, v219, v218 row_ror:8 row_mask:0xf bank_mask:0xf
	v_pk_mul_f32 v[166:167], v[92:93], v[166:167]
	v_add_f32_dpp v224, v224, v224 row_half_mirror row_mask:0xf bank_mask:0xf
	v_add_f32_dpp v220, v220, v220 quad_perm:[1,0,3,2] row_mask:0xf bank_mask:0xf
	v_pk_mul_f32 v[168:169], v[90:91], v[168:169]
	v_pk_mul_f32 v[170:171], v[92:93], v[170:171]
	v_add_f32_dpp v220, v220, v220 quad_perm:[2,3,0,1] row_mask:0xf bank_mask:0xf
	ds_write_b32 v209, v224 offset:49152
	v_add_u32_e32 v209, s12, v209
	v_pk_fma_f32 v[164:165], v[86:87], v[98:99], v[164:165] op_sel_hi:[1,0,1]
	v_pk_fma_f32 v[166:167], v[88:89], v[98:99], v[166:167] op_sel_hi:[1,0,1]
	v_add_f32_dpp v220, v220, v220 row_half_mirror row_mask:0xf bank_mask:0xf
	v_pk_fma_f32 v[168:169], v[86:87], v[100:101], v[168:169] op_sel_hi:[1,0,1]
	v_pk_fma_f32 v[170:171], v[88:89], v[100:101], v[170:171] op_sel_hi:[1,0,1]
	v_mov_b32_dpp v222, v220 row_ror:8 row_mask:0xf bank_mask:0xf
	v_pk_fma_f32 v[164:165], v[82:83], v[220:221], v[164:165] op_sel_hi:[1,0,1] neg_lo:[0,1,0] neg_hi:[0,1,0]
	v_pk_fma_f32 v[166:167], v[84:85], v[220:221], v[166:167] op_sel_hi:[1,0,1] neg_lo:[0,1,0] neg_hi:[0,1,0]
	v_pk_fma_f32 v[168:169], v[82:83], v[222:223], v[168:169] op_sel_hi:[1,0,1] neg_lo:[0,1,0] neg_hi:[0,1,0]
	v_pk_fma_f32 v[170:171], v[84:85], v[222:223], v[170:171] op_sel_hi:[1,0,1] neg_lo:[0,1,0] neg_hi:[0,1,0]
	v_pk_mul_f32 v[216:217], v[164:165], v[94:95]
	v_pk_mul_f32 v[94:95], v[168:169], v[94:95]
	v_pk_fma_f32 v[216:217], v[166:167], v[96:97], v[216:217]
	v_pk_fma_f32 v[94:95], v[170:171], v[96:97], v[94:95]
	v_add_f32_e32 v226, v216, v217
	v_add_f32_e32 v227, v94, v95
	s_waitcnt lgkmcnt(0)
	ds_read_b128 v[78:81], v207 offset:16640
	ds_read_b128 v[82:85], v207 offset:41216
	ds_read_b128 v[86:89], v207 offset:24832
	ds_read_b128 v[90:93], v207 offset:33024
	ds_read_b128 v[94:97], v207 offset:256
	ds_read_b32 v98, v208 offset:8448
	ds_read_b32 v100, v211 offset:8448
	v_pk_mul_f32 v[212:213], v[164:165], v[118:119]
	v_pk_mul_f32 v[118:119], v[168:169], v[118:119]
	v_add_f32_dpp v224, v227, v226 row_ror:8 row_mask:0xf bank_mask:0xf
	v_pk_fma_f32 v[212:213], v[166:167], v[120:121], v[212:213]
	v_pk_fma_f32 v[118:119], v[170:171], v[120:121], v[118:119]
	v_add_f32_dpp v224, v224, v224 quad_perm:[1,0,3,2] row_mask:0xf bank_mask:0xf
	v_add_f32_e32 v218, v212, v213
	v_add_f32_e32 v219, v118, v119
	v_pk_mul_f32 v[164:165], v[130:131], v[164:165]
	v_add_f32_dpp v224, v224, v224 quad_perm:[2,3,0,1] row_mask:0xf bank_mask:0xf
	v_add_f32_dpp v220, v219, v218 row_ror:8 row_mask:0xf bank_mask:0xf
	v_pk_mul_f32 v[166:167], v[132:133], v[166:167]
	v_add_f32_dpp v224, v224, v224 row_half_mirror row_mask:0xf bank_mask:0xf
	v_add_f32_dpp v220, v220, v220 quad_perm:[1,0,3,2] row_mask:0xf bank_mask:0xf
	v_pk_mul_f32 v[168:169], v[130:131], v[168:169]
	v_pk_mul_f32 v[170:171], v[132:133], v[170:171]
	v_add_f32_dpp v220, v220, v220 quad_perm:[2,3,0,1] row_mask:0xf bank_mask:0xf
	ds_write_b32 v209, v224 offset:49920
	v_pk_fma_f32 v[164:165], v[126:127], v[138:139], v[164:165] op_sel_hi:[1,0,1]
	v_pk_fma_f32 v[166:167], v[128:129], v[138:139], v[166:167] op_sel_hi:[1,0,1]
	v_add_f32_dpp v220, v220, v220 row_half_mirror row_mask:0xf bank_mask:0xf
	v_pk_fma_f32 v[168:169], v[126:127], v[140:141], v[168:169] op_sel_hi:[1,0,1]
	v_pk_fma_f32 v[170:171], v[128:129], v[140:141], v[170:171] op_sel_hi:[1,0,1]
	v_mov_b32_dpp v222, v220 row_ror:8 row_mask:0xf bank_mask:0xf
	v_pk_fma_f32 v[164:165], v[122:123], v[220:221], v[164:165] op_sel_hi:[1,0,1] neg_lo:[0,1,0] neg_hi:[0,1,0]
	v_pk_fma_f32 v[166:167], v[124:125], v[220:221], v[166:167] op_sel_hi:[1,0,1] neg_lo:[0,1,0] neg_hi:[0,1,0]
	v_pk_fma_f32 v[168:169], v[122:123], v[222:223], v[168:169] op_sel_hi:[1,0,1] neg_lo:[0,1,0] neg_hi:[0,1,0]
	v_pk_fma_f32 v[170:171], v[124:125], v[222:223], v[170:171] op_sel_hi:[1,0,1] neg_lo:[0,1,0] neg_hi:[0,1,0]
	v_pk_mul_f32 v[216:217], v[164:165], v[134:135]
	v_pk_mul_f32 v[134:135], v[168:169], v[134:135]
	v_pk_fma_f32 v[216:217], v[166:167], v[136:137], v[216:217]
	v_pk_fma_f32 v[134:135], v[170:171], v[136:137], v[134:135]
	v_add_f32_e32 v226, v216, v217
	v_add_f32_e32 v227, v134, v135
	s_waitcnt lgkmcnt(0)
	ds_read_b128 v[118:121], v207 offset:16384
	ds_read_b128 v[122:125], v207 offset:40960
	ds_read_b128 v[126:129], v207 offset:24576
	ds_read_b128 v[130:133], v207 offset:32768
	ds_read_b128 v[134:137], v207 offset:0
	ds_read_b32 v138, v208 offset:8192
	ds_read_b32 v140, v211 offset:8192
	v_pk_mul_f32 v[212:213], v[164:165], v[78:79]
	v_pk_mul_f32 v[78:79], v[168:169], v[78:79]
	v_add_f32_dpp v224, v227, v226 row_ror:8 row_mask:0xf bank_mask:0xf
	v_pk_fma_f32 v[212:213], v[166:167], v[80:81], v[212:213]
	v_pk_fma_f32 v[78:79], v[170:171], v[80:81], v[78:79]
	v_add_f32_dpp v224, v224, v224 quad_perm:[1,0,3,2] row_mask:0xf bank_mask:0xf
	v_add_f32_e32 v218, v212, v213
	v_add_f32_e32 v219, v78, v79
	v_pk_mul_f32 v[164:165], v[90:91], v[164:165]
	v_add_f32_dpp v224, v224, v224 quad_perm:[2,3,0,1] row_mask:0xf bank_mask:0xf
	v_add_f32_dpp v220, v219, v218 row_ror:8 row_mask:0xf bank_mask:0xf
	v_pk_mul_f32 v[166:167], v[92:93], v[166:167]
	v_add_f32_dpp v224, v224, v224 row_half_mirror row_mask:0xf bank_mask:0xf
	v_add_f32_dpp v220, v220, v220 quad_perm:[1,0,3,2] row_mask:0xf bank_mask:0xf
	v_pk_mul_f32 v[168:169], v[90:91], v[168:169]
	v_pk_mul_f32 v[170:171], v[92:93], v[170:171]
	v_add_f32_dpp v220, v220, v220 quad_perm:[2,3,0,1] row_mask:0xf bank_mask:0xf
	ds_write_b32 v209, v224 offset:49664
	v_pk_fma_f32 v[164:165], v[86:87], v[98:99], v[164:165] op_sel_hi:[1,0,1]
	v_pk_fma_f32 v[166:167], v[88:89], v[98:99], v[166:167] op_sel_hi:[1,0,1]
	v_add_f32_dpp v220, v220, v220 row_half_mirror row_mask:0xf bank_mask:0xf
	v_pk_fma_f32 v[168:169], v[86:87], v[100:101], v[168:169] op_sel_hi:[1,0,1]
	v_pk_fma_f32 v[170:171], v[88:89], v[100:101], v[170:171] op_sel_hi:[1,0,1]
	v_mov_b32_dpp v222, v220 row_ror:8 row_mask:0xf bank_mask:0xf
	v_pk_fma_f32 v[164:165], v[82:83], v[220:221], v[164:165] op_sel_hi:[1,0,1] neg_lo:[0,1,0] neg_hi:[0,1,0]
	v_pk_fma_f32 v[166:167], v[84:85], v[220:221], v[166:167] op_sel_hi:[1,0,1] neg_lo:[0,1,0] neg_hi:[0,1,0]
	v_pk_fma_f32 v[168:169], v[82:83], v[222:223], v[168:169] op_sel_hi:[1,0,1] neg_lo:[0,1,0] neg_hi:[0,1,0]
	v_pk_fma_f32 v[170:171], v[84:85], v[222:223], v[170:171] op_sel_hi:[1,0,1] neg_lo:[0,1,0] neg_hi:[0,1,0]
	v_pk_mul_f32 v[216:217], v[164:165], v[94:95]
	v_pk_mul_f32 v[94:95], v[168:169], v[94:95]
	v_pk_fma_f32 v[216:217], v[166:167], v[96:97], v[216:217]
	v_pk_fma_f32 v[94:95], v[170:171], v[96:97], v[94:95]
	v_add_f32_e32 v226, v216, v217
	v_add_f32_e32 v227, v94, v95
	s_waitcnt lgkmcnt(0)
	s_cmp_eq_u32 s11, 7
	s_cbranch_scc1 .Lscan_rev_nopf
	v_add_u32_e32 v207, s12, v207
	v_add_u32_e32 v208, s12, v208
	v_add_u32_e32 v211, s12, v211
	ds_read_b128 v[78:81], v207 offset:17152
	ds_read_b128 v[82:85], v207 offset:41728
	ds_read_b128 v[86:89], v207 offset:25344
	ds_read_b128 v[90:93], v207 offset:33536
	ds_read_b128 v[94:97], v207 offset:768
	ds_read_b32 v98, v208 offset:8960
	ds_read_b32 v100, v211 offset:8960
.Lscan_rev_nopf:
	v_pk_mul_f32 v[212:213], v[164:165], v[118:119]
	v_pk_mul_f32 v[118:119], v[168:169], v[118:119]
	v_add_f32_dpp v224, v227, v226 row_ror:8 row_mask:0xf bank_mask:0xf
	v_pk_fma_f32 v[212:213], v[166:167], v[120:121], v[212:213]
	v_pk_fma_f32 v[118:119], v[170:171], v[120:121], v[118:119]
	v_add_f32_dpp v224, v224, v224 quad_perm:[1,0,3,2] row_mask:0xf bank_mask:0xf
	v_add_f32_e32 v218, v212, v213
	v_add_f32_e32 v219, v118, v119
	v_pk_mul_f32 v[164:165], v[130:131], v[164:165]
	v_add_f32_dpp v224, v224, v224 quad_perm:[2,3,0,1] row_mask:0xf bank_mask:0xf
	v_add_f32_dpp v220, v219, v218 row_ror:8 row_mask:0xf bank_mask:0xf
	v_pk_mul_f32 v[166:167], v[132:133], v[166:167]
	v_add_f32_dpp v224, v224, v224 row_half_mirror row_mask:0xf bank_mask:0xf
	v_add_f32_dpp v220, v220, v220 quad_perm:[1,0,3,2] row_mask:0xf bank_mask:0xf
	v_pk_mul_f32 v[168:169], v[130:131], v[168:169]
	v_pk_mul_f32 v[170:171], v[132:133], v[170:171]
	v_add_f32_dpp v220, v220, v220 quad_perm:[2,3,0,1] row_mask:0xf bank_mask:0xf
	ds_write_b32 v209, v224 offset:49408
	v_pk_fma_f32 v[164:165], v[126:127], v[138:139], v[164:165] op_sel_hi:[1,0,1]
	v_pk_fma_f32 v[166:167], v[128:129], v[138:139], v[166:167] op_sel_hi:[1,0,1]
	v_add_f32_dpp v220, v220, v220 row_half_mirror row_mask:0xf bank_mask:0xf
	v_pk_fma_f32 v[168:169], v[126:127], v[140:141], v[168:169] op_sel_hi:[1,0,1]
	v_pk_fma_f32 v[170:171], v[128:129], v[140:141], v[170:171] op_sel_hi:[1,0,1]
	v_mov_b32_dpp v222, v220 row_ror:8 row_mask:0xf bank_mask:0xf
	v_pk_fma_f32 v[164:165], v[122:123], v[220:221], v[164:165] op_sel_hi:[1,0,1] neg_lo:[0,1,0] neg_hi:[0,1,0]
	v_pk_fma_f32 v[166:167], v[124:125], v[220:221], v[166:167] op_sel_hi:[1,0,1] neg_lo:[0,1,0] neg_hi:[0,1,0]
	v_pk_fma_f32 v[168:169], v[122:123], v[222:223], v[168:169] op_sel_hi:[1,0,1] neg_lo:[0,1,0] neg_hi:[0,1,0]
	v_pk_fma_f32 v[170:171], v[124:125], v[222:223], v[170:171] op_sel_hi:[1,0,1] neg_lo:[0,1,0] neg_hi:[0,1,0]
	v_pk_mul_f32 v[216:217], v[164:165], v[134:135]
	v_pk_mul_f32 v[134:135], v[168:169], v[134:135]
	v_pk_fma_f32 v[216:217], v[166:167], v[136:137], v[216:217]
	v_pk_fma_f32 v[134:135], v[170:171], v[136:137], v[134:135]
	v_add_f32_e32 v226, v216, v217
	v_add_f32_e32 v227, v134, v135
	s_add_i32 s11, s11, 1
	s_cmp_lg_u32 s11, 8
	s_cbranch_scc1 .Lscan_rev_loop
	s_nop 1
	v_add_f32_dpp v224, v227, v226 row_ror:8 row_mask:0xf bank_mask:0xf
	s_nop 1
	v_add_f32_dpp v224, v224, v224 quad_perm:[1,0,3,2] row_mask:0xf bank_mask:0xf
	s_nop 1
	v_add_f32_dpp v224, v224, v224 quad_perm:[2,3,0,1] row_mask:0xf bank_mask:0xf
	s_nop 1
	v_add_f32_dpp v224, v224, v224 row_half_mirror row_mask:0xf bank_mask:0xf
	ds_write_b32 v209, v224 offset:49152
